# phase-4 mid-stream gate hook software-pipelined (next row group's loads issued before current group's VALU) on top of p3a/EpiResid edits
# speedup vs baseline: 1.0062x; 1.0062x over previous
.LBB0_953:
	s_cmpk_lg_i32 s20, 0x1000
	s_cbranch_scc1 .LBB0_952
	v_mov_b32_e32 v151, v1
	v_mov_b32_e32 v150, v156
	v_mov_b64_e32 v[154:155], s[10:11]
	v_lshl_add_u32 v150, v150, 3, s46
	v_add_u32_e32 v161, s47, v151
	v_ashrrev_i32_e32 v151, 31, v150
	v_mov_b64_e32 v[152:153], s[2:3]
	v_lshlrev_b64 v[150:151], 1, v[150:151]
	v_mad_i64_i32 v[162:163], s[22:23], v161, s39, v[154:155]
	v_mad_i64_i32 v[166:167], s[22:23], v161, s39, v[152:153]
	v_lshl_add_u64 v[170:171], v[162:163], 0, v[150:151]
	global_load_dwordx4 v[162:165], v[170:171], off
	v_lshl_add_u64 v[174:175], v[166:167], 0, v[150:151]
	global_load_dwordx4 v[166:169], v[174:175], off
	s_nop 0
	global_load_dwordx4 v[170:173], v[170:171], off offset:256
	s_nop 0
	global_load_dwordx4 v[174:177], v[174:175], off offset:256
	v_add_u32_e32 v230, 16, v161
	v_mad_i64_i32 v[234:235], s[22:23], v230, s39, v[152:153]
	v_mad_i64_i32 v[230:231], s[22:23], v230, s39, v[154:155]
	v_lshl_add_u64 v[238:239], v[230:231], 0, v[150:151]
	global_load_dwordx4 v[230:233], v[238:239], off
	v_lshl_add_u64 v[242:243], v[234:235], 0, v[150:151]
	global_load_dwordx4 v[234:237], v[242:243], off
	s_nop 0
	global_load_dwordx4 v[238:241], v[238:239], off offset:256
	s_nop 0
	global_load_dwordx4 v[242:245], v[242:243], off offset:256
	s_waitcnt vmcnt(4)
	v_lshlrev_b32_e32 v178, 16, v166
	v_lshlrev_b32_e32 v180, 16, v162
	v_and_b32_e32 v181, 0xffff0000, v162
	v_lshlrev_b32_e32 v182, 16, v163
	v_and_b32_e32 v183, 0xffff0000, v163
	v_and_b32_e32 v179, 0xffff0000, v166
	v_lshlrev_b32_e32 v162, 16, v167
	v_and_b32_e32 v163, 0xffff0000, v167
	v_lshlrev_b32_e32 v184, 16, v164
	v_and_b32_e32 v185, 0xffff0000, v164
	v_lshlrev_b32_e32 v166, 16, v168
	v_and_b32_e32 v167, 0xffff0000, v168
	v_lshlrev_b32_e32 v186, 16, v165
	v_and_b32_e32 v187, 0xffff0000, v165
	v_lshlrev_b32_e32 v164, 16, v169
	v_and_b32_e32 v165, 0xffff0000, v169
	v_lshlrev_b32_e32 v188, 16, v170
	v_and_b32_e32 v189, 0xffff0000, v170
	v_lshlrev_b32_e32 v168, 16, v174
	v_and_b32_e32 v169, 0xffff0000, v174
	v_lshlrev_b32_e32 v174, 16, v171
	v_and_b32_e32 v190, 0xffff0000, v171
	v_lshlrev_b32_e32 v170, 16, v175
	v_and_b32_e32 v171, 0xffff0000, v175
	v_lshlrev_b32_e32 v175, 16, v172
	v_max_f32_e32 v180, v180, v180
	v_max_f32_e32 v181, v181, v181
	v_max_f32_e32 v182, v182, v182
	v_max_f32_e32 v183, v183, v183
	v_max_f32_e32 v184, v184, v184
	v_max_f32_e32 v185, v185, v185
	v_max_f32_e32 v186, v186, v186
	v_max_f32_e32 v187, v187, v187
	v_max_f32_e32 v174, v174, v174
	v_max_f32_e32 v175, v175, v175
	v_max_f32_e32 v180, 0xda24260, v180
	v_max_f32_e32 v181, 0xda24260, v181
	v_max_f32_e32 v182, 0xda24260, v182
	v_max_f32_e32 v183, 0xda24260, v183
	v_max_f32_e32 v184, 0xda24260, v184
	v_max_f32_e32 v185, 0xda24260, v185
	v_max_f32_e32 v186, 0xda24260, v186
	v_max_f32_e32 v187, 0xda24260, v187
	v_max_f32_e32 v191, 0xda24260, v174
	v_max_f32_e32 v192, 0xda24260, v175
	v_rcp_f32_e32 v174, v180
	v_rcp_f32_e32 v175, v181
	v_rcp_f32_e32 v180, v182
	v_rcp_f32_e32 v181, v183
	v_rcp_f32_e32 v182, v184
	v_rcp_f32_e32 v183, v185
	v_rcp_f32_e32 v184, v186
	v_rcp_f32_e32 v185, v187
	v_and_b32_e32 v172, 0xffff0000, v172
	v_pk_mul_f32 v[162:163], v[180:181], v[162:163]
	v_max_f32_e32 v188, v188, v188
	v_max_f32_e32 v189, v189, v189
	v_max_f32_e32 v190, v190, v190
	v_pk_mul_f32 v[164:165], v[184:185], v[164:165]
	v_pk_mul_f32 v[128:129], v[128:129], v[162:163]
	v_max_f32_e32 v162, v172, v172
	v_max_f32_e32 v188, 0xda24260, v188
	v_max_f32_e32 v189, 0xda24260, v189
	v_max_f32_e32 v190, 0xda24260, v190
	v_pk_mul_f32 v[124:125], v[124:125], v[164:165]
	v_max_f32_e32 v162, 0xda24260, v162
	v_lshlrev_b32_e32 v164, 16, v173
	v_and_b32_e32 v165, 0xffff0000, v173
	v_rcp_f32_e32 v186, v188
	v_rcp_f32_e32 v187, v189
	v_rcp_f32_e32 v188, v191
	v_rcp_f32_e32 v189, v190
	v_rcp_f32_e32 v190, v192
	v_rcp_f32_e32 v191, v162
	v_max_f32_e32 v164, v164, v164
	v_max_f32_e32 v165, v165, v165
	v_max_f32_e32 v164, 0xda24260, v164
	v_max_f32_e32 v165, 0xda24260, v165
	v_rcp_f32_e32 v164, v164
	v_rcp_f32_e32 v165, v165
	v_lshlrev_b32_e32 v162, 16, v176
	v_and_b32_e32 v163, 0xffff0000, v176
	v_pk_mul_f32 v[162:163], v[190:191], v[162:163]
	v_pk_mul_f32 v[174:175], v[174:175], v[178:179]
	v_pk_mul_f32 v[110:111], v[110:111], v[162:163]
	v_lshlrev_b32_e32 v162, 16, v177
	v_and_b32_e32 v163, 0xffff0000, v177
	v_pk_mul_f32 v[166:167], v[182:183], v[166:167]
	v_pk_mul_f32 v[168:169], v[186:187], v[168:169]
	v_pk_mul_f32 v[170:171], v[188:189], v[170:171]
	v_pk_mul_f32 v[162:163], v[164:165], v[162:163]
	v_pk_mul_f32 v[126:127], v[126:127], v[174:175]
	v_pk_mul_f32 v[122:123], v[122:123], v[166:167]
	v_pk_mul_f32 v[118:119], v[118:119], v[168:169]
	v_pk_mul_f32 v[120:121], v[120:121], v[170:171]
	v_pk_mul_f32 v[112:113], v[112:113], v[162:163]
	v_add_u32_e32 v162, 32, v161
	v_mad_i64_i32 v[166:167], s[22:23], v162, s39, v[152:153]
	v_mad_i64_i32 v[162:163], s[22:23], v162, s39, v[154:155]
	v_lshl_add_u64 v[170:171], v[162:163], 0, v[150:151]
	global_load_dwordx4 v[162:165], v[170:171], off
	v_lshl_add_u64 v[174:175], v[166:167], 0, v[150:151]
	global_load_dwordx4 v[166:169], v[174:175], off
	s_nop 0
	global_load_dwordx4 v[170:173], v[170:171], off offset:256
	s_nop 0
	global_load_dwordx4 v[174:177], v[174:175], off offset:256
	s_waitcnt vmcnt(4)
	v_lshlrev_b32_e32 v178, 16, v234
	v_lshlrev_b32_e32 v186, 16, v233
	v_and_b32_e32 v187, 0xffff0000, v233
	v_max_f32_e32 v186, v186, v186
	v_max_f32_e32 v187, v187, v187
	v_max_f32_e32 v186, 0xda24260, v186
	v_max_f32_e32 v187, 0xda24260, v187
	v_rcp_f32_e32 v186, v186
	v_rcp_f32_e32 v187, v187
	v_lshlrev_b32_e32 v182, 16, v231
	v_and_b32_e32 v183, 0xffff0000, v231
	v_lshlrev_b32_e32 v184, 16, v232
	v_and_b32_e32 v185, 0xffff0000, v232
	v_lshlrev_b32_e32 v232, 16, v237
	v_and_b32_e32 v233, 0xffff0000, v237
	v_lshlrev_b32_e32 v188, 16, v238
	v_and_b32_e32 v189, 0xffff0000, v238
	v_lshlrev_b32_e32 v190, 16, v239
	v_and_b32_e32 v191, 0xffff0000, v239
	v_lshlrev_b32_e32 v238, 16, v243
	v_and_b32_e32 v239, 0xffff0000, v243
	v_lshlrev_b32_e32 v243, 16, v240
	v_and_b32_e32 v240, 0xffff0000, v240
	v_max_f32_e32 v182, v182, v182
	v_max_f32_e32 v183, v183, v183
	v_max_f32_e32 v243, v243, v243
	v_max_f32_e32 v240, v240, v240
	v_max_f32_e32 v182, 0xda24260, v182
	v_max_f32_e32 v183, 0xda24260, v183
	v_pk_mul_f32 v[232:233], v[186:187], v[232:233]
	v_lshlrev_b32_e32 v180, 16, v230
	v_and_b32_e32 v181, 0xffff0000, v230
	v_max_f32_e32 v243, 0xda24260, v243
	v_max_f32_e32 v240, 0xda24260, v240
	v_rcp_f32_e32 v182, v182
	v_rcp_f32_e32 v183, v183
	v_pk_mul_f32 v[108:109], v[108:109], v[232:233]
	v_lshlrev_b32_e32 v232, 16, v241
	v_and_b32_e32 v233, 0xffff0000, v241
	v_max_f32_e32 v180, v180, v180
	v_max_f32_e32 v181, v181, v181
	v_max_f32_e32 v184, v184, v184
	v_max_f32_e32 v185, v185, v185
	v_max_f32_e32 v188, v188, v188
	v_max_f32_e32 v189, v189, v189
	v_max_f32_e32 v190, v190, v190
	v_max_f32_e32 v191, v191, v191
	v_rcp_f32_e32 v192, v243
	v_rcp_f32_e32 v193, v240
	v_max_f32_e32 v232, v232, v232
	v_max_f32_e32 v233, v233, v233
	v_max_f32_e32 v180, 0xda24260, v180
	v_max_f32_e32 v181, 0xda24260, v181
	v_max_f32_e32 v184, 0xda24260, v184
	v_max_f32_e32 v185, 0xda24260, v185
	v_max_f32_e32 v188, 0xda24260, v188
	v_max_f32_e32 v189, 0xda24260, v189
	v_max_f32_e32 v190, 0xda24260, v190
	v_max_f32_e32 v191, 0xda24260, v191
	v_max_f32_e32 v232, 0xda24260, v232
	v_max_f32_e32 v233, 0xda24260, v233
	v_lshlrev_b32_e32 v230, 16, v235
	v_and_b32_e32 v231, 0xffff0000, v235
	v_rcp_f32_e32 v180, v180
	v_rcp_f32_e32 v181, v181
	v_rcp_f32_e32 v184, v184
	v_rcp_f32_e32 v185, v185
	v_rcp_f32_e32 v188, v188
	v_rcp_f32_e32 v189, v189
	v_rcp_f32_e32 v190, v190
	v_rcp_f32_e32 v191, v191
	v_rcp_f32_e32 v232, v232
	v_rcp_f32_e32 v233, v233
	v_and_b32_e32 v179, 0xffff0000, v234
	v_lshlrev_b32_e32 v234, 16, v236
	v_and_b32_e32 v235, 0xffff0000, v236
	v_lshlrev_b32_e32 v236, 16, v242
	v_and_b32_e32 v237, 0xffff0000, v242
	v_lshlrev_b32_e32 v242, 16, v244
	v_pk_mul_f32 v[230:231], v[182:183], v[230:231]
	v_and_b32_e32 v243, 0xffff0000, v244
	v_pk_mul_f32 v[116:117], v[116:117], v[230:231]
	v_pk_mul_f32 v[230:231], v[192:193], v[242:243]
	v_pk_mul_f32 v[178:179], v[180:181], v[178:179]
	v_pk_mul_f32 v[94:95], v[94:95], v[230:231]
	v_lshlrev_b32_e32 v230, 16, v245
	v_and_b32_e32 v231, 0xffff0000, v245
	v_pk_mul_f32 v[234:235], v[184:185], v[234:235]
	v_pk_mul_f32 v[236:237], v[188:189], v[236:237]
	v_pk_mul_f32 v[238:239], v[190:191], v[238:239]
	v_pk_mul_f32 v[230:231], v[232:233], v[230:231]
	v_pk_mul_f32 v[114:115], v[114:115], v[178:179]
	v_pk_mul_f32 v[106:107], v[106:107], v[234:235]
	v_pk_mul_f32 v[102:103], v[102:103], v[236:237]
	v_pk_mul_f32 v[104:105], v[104:105], v[238:239]
	v_pk_mul_f32 v[96:97], v[96:97], v[230:231]
	v_add_u32_e32 v230, 48, v161
	v_mad_i64_i32 v[234:235], s[22:23], v230, s39, v[152:153]
	v_mad_i64_i32 v[230:231], s[22:23], v230, s39, v[154:155]
	v_lshl_add_u64 v[238:239], v[230:231], 0, v[150:151]
	global_load_dwordx4 v[230:233], v[238:239], off
	v_lshl_add_u64 v[242:243], v[234:235], 0, v[150:151]
	global_load_dwordx4 v[234:237], v[242:243], off
	s_nop 0
	global_load_dwordx4 v[238:241], v[238:239], off offset:256
	s_nop 0
	global_load_dwordx4 v[242:245], v[242:243], off offset:256
	s_waitcnt vmcnt(4)
	v_lshlrev_b32_e32 v178, 16, v166
	v_lshlrev_b32_e32 v186, 16, v165
	v_and_b32_e32 v187, 0xffff0000, v165
	v_max_f32_e32 v186, v186, v186
	v_max_f32_e32 v187, v187, v187
	v_max_f32_e32 v186, 0xda24260, v186
	v_max_f32_e32 v187, 0xda24260, v187
	v_rcp_f32_e32 v186, v186
	v_rcp_f32_e32 v187, v187
	v_lshlrev_b32_e32 v182, 16, v163
	v_and_b32_e32 v183, 0xffff0000, v163
	v_lshlrev_b32_e32 v184, 16, v164
	v_and_b32_e32 v185, 0xffff0000, v164
	v_lshlrev_b32_e32 v164, 16, v169
	v_and_b32_e32 v165, 0xffff0000, v169
	v_lshlrev_b32_e32 v188, 16, v170
	v_and_b32_e32 v189, 0xffff0000, v170
	v_lshlrev_b32_e32 v190, 16, v171
	v_and_b32_e32 v191, 0xffff0000, v171
	v_lshlrev_b32_e32 v170, 16, v175
	v_and_b32_e32 v171, 0xffff0000, v175
	v_lshlrev_b32_e32 v175, 16, v172
	v_and_b32_e32 v172, 0xffff0000, v172
	v_max_f32_e32 v182, v182, v182
	v_max_f32_e32 v183, v183, v183
	v_max_f32_e32 v175, v175, v175
	v_max_f32_e32 v172, v172, v172
	v_max_f32_e32 v182, 0xda24260, v182
	v_max_f32_e32 v183, 0xda24260, v183
	v_pk_mul_f32 v[164:165], v[186:187], v[164:165]
	v_lshlrev_b32_e32 v180, 16, v162
	v_and_b32_e32 v181, 0xffff0000, v162
	v_max_f32_e32 v175, 0xda24260, v175
	v_max_f32_e32 v172, 0xda24260, v172
	v_rcp_f32_e32 v182, v182
	v_rcp_f32_e32 v183, v183
	v_pk_mul_f32 v[92:93], v[92:93], v[164:165]
	v_lshlrev_b32_e32 v164, 16, v173
	v_and_b32_e32 v165, 0xffff0000, v173
	v_max_f32_e32 v180, v180, v180
	v_max_f32_e32 v181, v181, v181
	v_max_f32_e32 v184, v184, v184
	v_max_f32_e32 v185, v185, v185
	v_max_f32_e32 v188, v188, v188
	v_max_f32_e32 v189, v189, v189
	v_max_f32_e32 v190, v190, v190
	v_max_f32_e32 v191, v191, v191
	v_rcp_f32_e32 v192, v175
	v_rcp_f32_e32 v193, v172
	v_max_f32_e32 v164, v164, v164
	v_max_f32_e32 v165, v165, v165
	v_max_f32_e32 v180, 0xda24260, v180
	v_max_f32_e32 v181, 0xda24260, v181
	v_max_f32_e32 v184, 0xda24260, v184
	v_max_f32_e32 v185, 0xda24260, v185
	v_max_f32_e32 v188, 0xda24260, v188
	v_max_f32_e32 v189, 0xda24260, v189
	v_max_f32_e32 v190, 0xda24260, v190
	v_max_f32_e32 v191, 0xda24260, v191
	v_max_f32_e32 v164, 0xda24260, v164
	v_max_f32_e32 v165, 0xda24260, v165
	v_lshlrev_b32_e32 v162, 16, v167
	v_and_b32_e32 v163, 0xffff0000, v167
	v_rcp_f32_e32 v180, v180
	v_rcp_f32_e32 v181, v181
	v_rcp_f32_e32 v184, v184
	v_rcp_f32_e32 v185, v185
	v_rcp_f32_e32 v188, v188
	v_rcp_f32_e32 v189, v189
	v_rcp_f32_e32 v190, v190
	v_rcp_f32_e32 v191, v191
	v_rcp_f32_e32 v164, v164
	v_rcp_f32_e32 v165, v165
	v_and_b32_e32 v179, 0xffff0000, v166
	v_lshlrev_b32_e32 v166, 16, v168
	v_and_b32_e32 v167, 0xffff0000, v168
	v_lshlrev_b32_e32 v168, 16, v174
	v_and_b32_e32 v169, 0xffff0000, v174
	v_lshlrev_b32_e32 v174, 16, v176
	v_pk_mul_f32 v[162:163], v[182:183], v[162:163]
	v_and_b32_e32 v175, 0xffff0000, v176
	v_pk_mul_f32 v[100:101], v[100:101], v[162:163]
	v_pk_mul_f32 v[162:163], v[192:193], v[174:175]
	v_pk_mul_f32 v[178:179], v[180:181], v[178:179]
	v_pk_mul_f32 v[78:79], v[78:79], v[162:163]
	v_lshlrev_b32_e32 v162, 16, v177
	v_and_b32_e32 v163, 0xffff0000, v177
	v_pk_mul_f32 v[166:167], v[184:185], v[166:167]
	v_pk_mul_f32 v[168:169], v[188:189], v[168:169]
	v_pk_mul_f32 v[170:171], v[190:191], v[170:171]
	v_pk_mul_f32 v[162:163], v[164:165], v[162:163]
	v_pk_mul_f32 v[98:99], v[98:99], v[178:179]
	v_pk_mul_f32 v[90:91], v[90:91], v[166:167]
	v_pk_mul_f32 v[86:87], v[86:87], v[168:169]
	v_pk_mul_f32 v[88:89], v[88:89], v[170:171]
	v_pk_mul_f32 v[80:81], v[80:81], v[162:163]
	v_add_u32_e32 v162, 0x80, v161
	v_mad_i64_i32 v[166:167], s[22:23], v162, s39, v[152:153]
	v_mad_i64_i32 v[162:163], s[22:23], v162, s39, v[154:155]
	v_lshl_add_u64 v[170:171], v[162:163], 0, v[150:151]
	global_load_dwordx4 v[162:165], v[170:171], off
	v_lshl_add_u64 v[174:175], v[166:167], 0, v[150:151]
	global_load_dwordx4 v[166:169], v[174:175], off
	s_nop 0
	global_load_dwordx4 v[170:173], v[170:171], off offset:256
	s_nop 0
	global_load_dwordx4 v[174:177], v[174:175], off offset:256
	s_waitcnt vmcnt(4)
	v_lshlrev_b32_e32 v178, 16, v234
	v_lshlrev_b32_e32 v186, 16, v233
	v_and_b32_e32 v187, 0xffff0000, v233
	v_max_f32_e32 v186, v186, v186
	v_max_f32_e32 v187, v187, v187
	v_max_f32_e32 v186, 0xda24260, v186
	v_max_f32_e32 v187, 0xda24260, v187
	v_rcp_f32_e32 v186, v186
	v_rcp_f32_e32 v187, v187
	v_lshlrev_b32_e32 v182, 16, v231
	v_and_b32_e32 v183, 0xffff0000, v231
	v_lshlrev_b32_e32 v184, 16, v232
	v_and_b32_e32 v185, 0xffff0000, v232
	v_lshlrev_b32_e32 v232, 16, v237
	v_and_b32_e32 v233, 0xffff0000, v237
	v_lshlrev_b32_e32 v188, 16, v238
	v_and_b32_e32 v189, 0xffff0000, v238
	v_lshlrev_b32_e32 v190, 16, v239
	v_and_b32_e32 v191, 0xffff0000, v239
	v_lshlrev_b32_e32 v238, 16, v243
	v_and_b32_e32 v239, 0xffff0000, v243
	v_lshlrev_b32_e32 v243, 16, v240
	v_and_b32_e32 v240, 0xffff0000, v240
	v_max_f32_e32 v182, v182, v182
	v_max_f32_e32 v183, v183, v183
	v_max_f32_e32 v243, v243, v243
	v_max_f32_e32 v240, v240, v240
	v_max_f32_e32 v182, 0xda24260, v182
	v_max_f32_e32 v183, 0xda24260, v183
	v_pk_mul_f32 v[232:233], v[186:187], v[232:233]
	v_lshlrev_b32_e32 v180, 16, v230
	v_and_b32_e32 v181, 0xffff0000, v230
	v_max_f32_e32 v243, 0xda24260, v243
	v_max_f32_e32 v240, 0xda24260, v240
	v_rcp_f32_e32 v182, v182
	v_rcp_f32_e32 v183, v183
	v_pk_mul_f32 v[76:77], v[76:77], v[232:233]
	v_lshlrev_b32_e32 v232, 16, v241
	v_and_b32_e32 v233, 0xffff0000, v241
	v_max_f32_e32 v180, v180, v180
	v_max_f32_e32 v181, v181, v181
	v_max_f32_e32 v184, v184, v184
	v_max_f32_e32 v185, v185, v185
	v_max_f32_e32 v188, v188, v188
	v_max_f32_e32 v189, v189, v189
	v_max_f32_e32 v190, v190, v190
	v_max_f32_e32 v191, v191, v191
	v_rcp_f32_e32 v192, v243
	v_rcp_f32_e32 v193, v240
	v_max_f32_e32 v232, v232, v232
	v_max_f32_e32 v233, v233, v233
	v_max_f32_e32 v180, 0xda24260, v180
	v_max_f32_e32 v181, 0xda24260, v181
	v_max_f32_e32 v184, 0xda24260, v184
	v_max_f32_e32 v185, 0xda24260, v185
	v_max_f32_e32 v188, 0xda24260, v188
	v_max_f32_e32 v189, 0xda24260, v189
	v_max_f32_e32 v190, 0xda24260, v190
	v_max_f32_e32 v191, 0xda24260, v191
	v_max_f32_e32 v232, 0xda24260, v232
	v_max_f32_e32 v233, 0xda24260, v233
	v_lshlrev_b32_e32 v230, 16, v235
	v_and_b32_e32 v231, 0xffff0000, v235
	v_rcp_f32_e32 v180, v180
	v_rcp_f32_e32 v181, v181
	v_rcp_f32_e32 v184, v184
	v_rcp_f32_e32 v185, v185
	v_rcp_f32_e32 v188, v188
	v_rcp_f32_e32 v189, v189
	v_rcp_f32_e32 v190, v190
	v_rcp_f32_e32 v191, v191
	v_rcp_f32_e32 v232, v232
	v_rcp_f32_e32 v233, v233
	v_and_b32_e32 v179, 0xffff0000, v234
	v_lshlrev_b32_e32 v234, 16, v236
	v_and_b32_e32 v235, 0xffff0000, v236
	v_lshlrev_b32_e32 v236, 16, v242
	v_and_b32_e32 v237, 0xffff0000, v242
	v_lshlrev_b32_e32 v242, 16, v244
	v_pk_mul_f32 v[230:231], v[182:183], v[230:231]
	v_and_b32_e32 v243, 0xffff0000, v244
	v_pk_mul_f32 v[84:85], v[84:85], v[230:231]
	v_pk_mul_f32 v[230:231], v[192:193], v[242:243]
	v_pk_mul_f32 v[178:179], v[180:181], v[178:179]
	v_pk_mul_f32 v[66:67], v[66:67], v[230:231]
	v_lshlrev_b32_e32 v230, 16, v245
	v_and_b32_e32 v231, 0xffff0000, v245
	v_pk_mul_f32 v[234:235], v[184:185], v[234:235]
	v_pk_mul_f32 v[236:237], v[188:189], v[236:237]
	v_pk_mul_f32 v[238:239], v[190:191], v[238:239]
	v_pk_mul_f32 v[230:231], v[232:233], v[230:231]
	v_pk_mul_f32 v[82:83], v[82:83], v[178:179]
	v_pk_mul_f32 v[74:75], v[74:75], v[234:235]
	v_pk_mul_f32 v[70:71], v[70:71], v[236:237]
	v_pk_mul_f32 v[72:73], v[72:73], v[238:239]
	v_pk_mul_f32 v[68:69], v[68:69], v[230:231]
	v_add_u32_e32 v230, 0x90, v161
	v_mad_i64_i32 v[234:235], s[22:23], v230, s39, v[152:153]
	v_mad_i64_i32 v[230:231], s[22:23], v230, s39, v[154:155]
	v_lshl_add_u64 v[238:239], v[230:231], 0, v[150:151]
	global_load_dwordx4 v[230:233], v[238:239], off
	v_lshl_add_u64 v[242:243], v[234:235], 0, v[150:151]
	global_load_dwordx4 v[234:237], v[242:243], off
	s_nop 0
	global_load_dwordx4 v[238:241], v[238:239], off offset:256
	s_nop 0
	global_load_dwordx4 v[242:245], v[242:243], off offset:256
	s_waitcnt vmcnt(4)
	v_lshlrev_b32_e32 v178, 16, v166
	v_lshlrev_b32_e32 v186, 16, v165
	v_and_b32_e32 v187, 0xffff0000, v165
	v_max_f32_e32 v186, v186, v186
	v_max_f32_e32 v187, v187, v187
	v_max_f32_e32 v186, 0xda24260, v186
	v_max_f32_e32 v187, 0xda24260, v187
	v_rcp_f32_e32 v186, v186
	v_rcp_f32_e32 v187, v187
	v_lshlrev_b32_e32 v182, 16, v163
	v_and_b32_e32 v183, 0xffff0000, v163
	v_lshlrev_b32_e32 v184, 16, v164
	v_and_b32_e32 v185, 0xffff0000, v164
	v_lshlrev_b32_e32 v164, 16, v169
	v_and_b32_e32 v165, 0xffff0000, v169
	v_lshlrev_b32_e32 v188, 16, v170
	v_and_b32_e32 v189, 0xffff0000, v170
	v_lshlrev_b32_e32 v190, 16, v171
	v_and_b32_e32 v191, 0xffff0000, v171
	v_lshlrev_b32_e32 v170, 16, v175
	v_and_b32_e32 v171, 0xffff0000, v175
	v_lshlrev_b32_e32 v175, 16, v172
	v_and_b32_e32 v172, 0xffff0000, v172
	v_max_f32_e32 v182, v182, v182
	v_max_f32_e32 v183, v183, v183
	v_max_f32_e32 v175, v175, v175
	v_max_f32_e32 v172, v172, v172
	v_max_f32_e32 v182, 0xda24260, v182
	v_max_f32_e32 v183, 0xda24260, v183
	v_pk_mul_f32 v[164:165], v[186:187], v[164:165]
	v_lshlrev_b32_e32 v180, 16, v162
	v_and_b32_e32 v181, 0xffff0000, v162
	v_max_f32_e32 v175, 0xda24260, v175
	v_max_f32_e32 v172, 0xda24260, v172
	v_rcp_f32_e32 v182, v182
	v_rcp_f32_e32 v183, v183
	v_pk_mul_f32 v[60:61], v[60:61], v[164:165]
	v_lshlrev_b32_e32 v164, 16, v173
	v_and_b32_e32 v165, 0xffff0000, v173
	v_max_f32_e32 v180, v180, v180
	v_max_f32_e32 v181, v181, v181
	v_max_f32_e32 v184, v184, v184
	v_max_f32_e32 v185, v185, v185
	v_max_f32_e32 v188, v188, v188
	v_max_f32_e32 v189, v189, v189
	v_max_f32_e32 v190, v190, v190
	v_max_f32_e32 v191, v191, v191
	v_rcp_f32_e32 v192, v175
	v_rcp_f32_e32 v193, v172
	v_max_f32_e32 v164, v164, v164
	v_max_f32_e32 v165, v165, v165
	v_max_f32_e32 v180, 0xda24260, v180
	v_max_f32_e32 v181, 0xda24260, v181
	v_max_f32_e32 v184, 0xda24260, v184
	v_max_f32_e32 v185, 0xda24260, v185
	v_max_f32_e32 v188, 0xda24260, v188
	v_max_f32_e32 v189, 0xda24260, v189
	v_max_f32_e32 v190, 0xda24260, v190
	v_max_f32_e32 v191, 0xda24260, v191
	v_max_f32_e32 v164, 0xda24260, v164
	v_max_f32_e32 v165, 0xda24260, v165
	v_lshlrev_b32_e32 v162, 16, v167
	v_and_b32_e32 v163, 0xffff0000, v167
	v_rcp_f32_e32 v180, v180
	v_rcp_f32_e32 v181, v181
	v_rcp_f32_e32 v184, v184
	v_rcp_f32_e32 v185, v185
	v_rcp_f32_e32 v188, v188
	v_rcp_f32_e32 v189, v189
	v_rcp_f32_e32 v190, v190
	v_rcp_f32_e32 v191, v191
	v_rcp_f32_e32 v164, v164
	v_rcp_f32_e32 v165, v165
	v_and_b32_e32 v179, 0xffff0000, v166
	v_lshlrev_b32_e32 v166, 16, v168
	v_and_b32_e32 v167, 0xffff0000, v168
	v_lshlrev_b32_e32 v168, 16, v174
	v_and_b32_e32 v169, 0xffff0000, v174
	v_lshlrev_b32_e32 v174, 16, v176
	v_pk_mul_f32 v[162:163], v[182:183], v[162:163]
	v_and_b32_e32 v175, 0xffff0000, v176
	v_pk_mul_f32 v[64:65], v[64:65], v[162:163]
	v_pk_mul_f32 v[162:163], v[192:193], v[174:175]
	v_pk_mul_f32 v[178:179], v[180:181], v[178:179]
	v_pk_mul_f32 v[46:47], v[46:47], v[162:163]
	v_lshlrev_b32_e32 v162, 16, v177
	v_and_b32_e32 v163, 0xffff0000, v177
	v_pk_mul_f32 v[166:167], v[184:185], v[166:167]
	v_pk_mul_f32 v[168:169], v[188:189], v[168:169]
	v_pk_mul_f32 v[170:171], v[190:191], v[170:171]
	v_pk_mul_f32 v[162:163], v[164:165], v[162:163]
	v_pk_mul_f32 v[62:63], v[62:63], v[178:179]
	v_pk_mul_f32 v[58:59], v[58:59], v[166:167]
	v_pk_mul_f32 v[54:55], v[54:55], v[168:169]
	v_pk_mul_f32 v[56:57], v[56:57], v[170:171]
	v_pk_mul_f32 v[48:49], v[48:49], v[162:163]
	v_add_u32_e32 v162, 0xa0, v161
	v_mad_i64_i32 v[166:167], s[22:23], v162, s39, v[152:153]
	v_mad_i64_i32 v[162:163], s[22:23], v162, s39, v[154:155]
	v_lshl_add_u64 v[170:171], v[162:163], 0, v[150:151]
	global_load_dwordx4 v[162:165], v[170:171], off
	v_lshl_add_u64 v[174:175], v[166:167], 0, v[150:151]
	global_load_dwordx4 v[166:169], v[174:175], off
	s_nop 0
	global_load_dwordx4 v[170:173], v[170:171], off offset:256
	s_nop 0
	global_load_dwordx4 v[174:177], v[174:175], off offset:256
	s_waitcnt vmcnt(4)
	v_lshlrev_b32_e32 v178, 16, v234
	v_lshlrev_b32_e32 v186, 16, v233
	v_and_b32_e32 v187, 0xffff0000, v233
	v_max_f32_e32 v186, v186, v186
	v_max_f32_e32 v187, v187, v187
	v_max_f32_e32 v186, 0xda24260, v186
	v_max_f32_e32 v187, 0xda24260, v187
	v_rcp_f32_e32 v186, v186
	v_rcp_f32_e32 v187, v187
	v_lshlrev_b32_e32 v182, 16, v231
	v_and_b32_e32 v183, 0xffff0000, v231
	v_lshlrev_b32_e32 v184, 16, v232
	v_and_b32_e32 v185, 0xffff0000, v232
	v_lshlrev_b32_e32 v232, 16, v237
	v_and_b32_e32 v233, 0xffff0000, v237
	v_lshlrev_b32_e32 v188, 16, v238
	v_and_b32_e32 v189, 0xffff0000, v238
	v_lshlrev_b32_e32 v190, 16, v239
	v_and_b32_e32 v191, 0xffff0000, v239
	v_lshlrev_b32_e32 v238, 16, v243
	v_and_b32_e32 v239, 0xffff0000, v243
	v_lshlrev_b32_e32 v243, 16, v240
	v_and_b32_e32 v240, 0xffff0000, v240
	v_max_f32_e32 v182, v182, v182
	v_max_f32_e32 v183, v183, v183
	v_max_f32_e32 v243, v243, v243
	v_max_f32_e32 v240, v240, v240
	v_max_f32_e32 v182, 0xda24260, v182
	v_max_f32_e32 v183, 0xda24260, v183
	v_pk_mul_f32 v[232:233], v[186:187], v[232:233]
	v_lshlrev_b32_e32 v180, 16, v230
	v_and_b32_e32 v181, 0xffff0000, v230
	v_max_f32_e32 v243, 0xda24260, v243
	v_max_f32_e32 v240, 0xda24260, v240
	v_rcp_f32_e32 v182, v182
	v_rcp_f32_e32 v183, v183
	v_pk_mul_f32 v[44:45], v[44:45], v[232:233]
	v_lshlrev_b32_e32 v232, 16, v241
	v_and_b32_e32 v233, 0xffff0000, v241
	v_max_f32_e32 v180, v180, v180
	v_max_f32_e32 v181, v181, v181
	v_max_f32_e32 v184, v184, v184
	v_max_f32_e32 v185, v185, v185
	v_max_f32_e32 v188, v188, v188
	v_max_f32_e32 v189, v189, v189
	v_max_f32_e32 v190, v190, v190
	v_max_f32_e32 v191, v191, v191
	v_rcp_f32_e32 v192, v243
	v_rcp_f32_e32 v193, v240
	v_max_f32_e32 v232, v232, v232
	v_max_f32_e32 v233, v233, v233
	v_max_f32_e32 v180, 0xda24260, v180
	v_max_f32_e32 v181, 0xda24260, v181
	v_max_f32_e32 v184, 0xda24260, v184
	v_max_f32_e32 v185, 0xda24260, v185
	v_max_f32_e32 v188, 0xda24260, v188
	v_max_f32_e32 v189, 0xda24260, v189
	v_max_f32_e32 v190, 0xda24260, v190
	v_max_f32_e32 v191, 0xda24260, v191
	v_max_f32_e32 v232, 0xda24260, v232
	v_max_f32_e32 v233, 0xda24260, v233
	v_lshlrev_b32_e32 v230, 16, v235
	v_and_b32_e32 v231, 0xffff0000, v235
	v_rcp_f32_e32 v180, v180
	v_rcp_f32_e32 v181, v181
	v_rcp_f32_e32 v184, v184
	v_rcp_f32_e32 v185, v185
	v_rcp_f32_e32 v188, v188
	v_rcp_f32_e32 v189, v189
	v_rcp_f32_e32 v190, v190
	v_rcp_f32_e32 v191, v191
	v_rcp_f32_e32 v232, v232
	v_rcp_f32_e32 v233, v233
	v_and_b32_e32 v179, 0xffff0000, v234
	v_lshlrev_b32_e32 v234, 16, v236
	v_and_b32_e32 v235, 0xffff0000, v236
	v_lshlrev_b32_e32 v236, 16, v242
	v_and_b32_e32 v237, 0xffff0000, v242
	v_lshlrev_b32_e32 v242, 16, v244
	v_pk_mul_f32 v[230:231], v[182:183], v[230:231]
	v_and_b32_e32 v243, 0xffff0000, v244
	v_pk_mul_f32 v[52:53], v[52:53], v[230:231]
	v_pk_mul_f32 v[230:231], v[192:193], v[242:243]
	v_pk_mul_f32 v[178:179], v[180:181], v[178:179]
	v_pk_mul_f32 v[30:31], v[30:31], v[230:231]
	v_lshlrev_b32_e32 v230, 16, v245
	v_and_b32_e32 v231, 0xffff0000, v245
	v_pk_mul_f32 v[234:235], v[184:185], v[234:235]
	v_pk_mul_f32 v[236:237], v[188:189], v[236:237]
	v_pk_mul_f32 v[238:239], v[190:191], v[238:239]
	v_pk_mul_f32 v[230:231], v[232:233], v[230:231]
	v_pk_mul_f32 v[50:51], v[50:51], v[178:179]
	v_pk_mul_f32 v[42:43], v[42:43], v[234:235]
	v_pk_mul_f32 v[38:39], v[38:39], v[236:237]
	v_pk_mul_f32 v[40:41], v[40:41], v[238:239]
	v_pk_mul_f32 v[32:33], v[32:33], v[230:231]
	s_waitcnt vmcnt(0)
	v_lshlrev_b32_e32 v178, 16, v166
	v_lshlrev_b32_e32 v186, 16, v165
	v_and_b32_e32 v187, 0xffff0000, v165
	v_max_f32_e32 v186, v186, v186
	v_max_f32_e32 v187, v187, v187
	v_max_f32_e32 v186, 0xda24260, v186
	v_max_f32_e32 v187, 0xda24260, v187
	v_rcp_f32_e32 v186, v186
	v_rcp_f32_e32 v187, v187
	v_lshlrev_b32_e32 v182, 16, v163
	v_and_b32_e32 v183, 0xffff0000, v163
	v_lshlrev_b32_e32 v184, 16, v164
	v_and_b32_e32 v185, 0xffff0000, v164
	v_lshlrev_b32_e32 v164, 16, v169
	v_and_b32_e32 v165, 0xffff0000, v169
	v_lshlrev_b32_e32 v188, 16, v170
	v_and_b32_e32 v189, 0xffff0000, v170
	v_lshlrev_b32_e32 v190, 16, v171
	v_and_b32_e32 v191, 0xffff0000, v171
	v_lshlrev_b32_e32 v170, 16, v175
	v_and_b32_e32 v171, 0xffff0000, v175
	v_lshlrev_b32_e32 v175, 16, v172
	v_and_b32_e32 v172, 0xffff0000, v172
	v_max_f32_e32 v182, v182, v182
	v_max_f32_e32 v183, v183, v183
	v_max_f32_e32 v175, v175, v175
	v_max_f32_e32 v172, v172, v172
	v_max_f32_e32 v182, 0xda24260, v182
	v_max_f32_e32 v183, 0xda24260, v183
	v_pk_mul_f32 v[164:165], v[186:187], v[164:165]
	v_lshlrev_b32_e32 v180, 16, v162
	v_and_b32_e32 v181, 0xffff0000, v162
	v_max_f32_e32 v175, 0xda24260, v175
	v_max_f32_e32 v172, 0xda24260, v172
	v_rcp_f32_e32 v182, v182
	v_rcp_f32_e32 v183, v183
	v_pk_mul_f32 v[28:29], v[28:29], v[164:165]
	v_lshlrev_b32_e32 v164, 16, v173
	v_and_b32_e32 v165, 0xffff0000, v173
	v_max_f32_e32 v180, v180, v180
	v_max_f32_e32 v181, v181, v181
	v_max_f32_e32 v184, v184, v184
	v_max_f32_e32 v185, v185, v185
	v_max_f32_e32 v188, v188, v188
	v_max_f32_e32 v189, v189, v189
	v_max_f32_e32 v190, v190, v190
	v_max_f32_e32 v191, v191, v191
	v_rcp_f32_e32 v192, v175
	v_rcp_f32_e32 v193, v172
	v_max_f32_e32 v164, v164, v164
	v_max_f32_e32 v165, v165, v165
	v_max_f32_e32 v180, 0xda24260, v180
	v_max_f32_e32 v181, 0xda24260, v181
	v_max_f32_e32 v184, 0xda24260, v184
	v_max_f32_e32 v185, 0xda24260, v185
	v_max_f32_e32 v188, 0xda24260, v188
	v_max_f32_e32 v189, 0xda24260, v189
	v_max_f32_e32 v190, 0xda24260, v190
	v_max_f32_e32 v191, 0xda24260, v191
	v_max_f32_e32 v164, 0xda24260, v164
	v_max_f32_e32 v165, 0xda24260, v165
	v_lshlrev_b32_e32 v162, 16, v167
	v_and_b32_e32 v163, 0xffff0000, v167
	v_rcp_f32_e32 v180, v180
	v_rcp_f32_e32 v181, v181
	v_rcp_f32_e32 v184, v184
	v_rcp_f32_e32 v185, v185
	v_rcp_f32_e32 v188, v188
	v_rcp_f32_e32 v189, v189
	v_rcp_f32_e32 v190, v190
	v_rcp_f32_e32 v191, v191
	v_rcp_f32_e32 v164, v164
	v_rcp_f32_e32 v165, v165
	v_and_b32_e32 v179, 0xffff0000, v166
	v_lshlrev_b32_e32 v166, 16, v168
	v_and_b32_e32 v167, 0xffff0000, v168
	v_lshlrev_b32_e32 v168, 16, v174
	v_and_b32_e32 v169, 0xffff0000, v174
	v_lshlrev_b32_e32 v174, 16, v176
	v_pk_mul_f32 v[162:163], v[182:183], v[162:163]
	v_and_b32_e32 v175, 0xffff0000, v176
	v_pk_mul_f32 v[36:37], v[36:37], v[162:163]
	v_pk_mul_f32 v[162:163], v[192:193], v[174:175]
	v_pk_mul_f32 v[178:179], v[180:181], v[178:179]
	v_pk_mul_f32 v[14:15], v[14:15], v[162:163]
	v_lshlrev_b32_e32 v162, 16, v177
	v_and_b32_e32 v163, 0xffff0000, v177
	v_pk_mul_f32 v[166:167], v[184:185], v[166:167]
	v_pk_mul_f32 v[168:169], v[188:189], v[168:169]
	v_pk_mul_f32 v[170:171], v[190:191], v[170:171]
	v_pk_mul_f32 v[162:163], v[164:165], v[162:163]
	v_pk_mul_f32 v[34:35], v[34:35], v[178:179]
	v_pk_mul_f32 v[26:27], v[26:27], v[166:167]
	v_pk_mul_f32 v[22:23], v[22:23], v[168:169]
	v_pk_mul_f32 v[24:25], v[24:25], v[170:171]
	v_pk_mul_f32 v[16:17], v[16:17], v[162:163]
	v_add_u32_e32 v161, 0xb0, v161
	v_mad_i64_i32 v[162:163], s[22:23], v161, s39, v[152:153]
	v_mad_i64_i32 v[152:153], s[22:23], v161, s39, v[154:155]
	v_lshl_add_u64 v[166:167], v[152:153], 0, v[150:151]
	global_load_dwordx4 v[152:155], v[166:167], off
	v_lshl_add_u64 v[150:151], v[162:163], 0, v[150:151]
	global_load_dwordx4 v[162:165], v[150:151], off
	s_nop 0
	global_load_dwordx4 v[166:169], v[166:167], off offset:256
	s_nop 0
	global_load_dwordx4 v[170:173], v[150:151], off offset:256
	s_waitcnt vmcnt(0)
	v_lshlrev_b32_e32 v150, 16, v162
	v_lshlrev_b32_e32 v175, 16, v153
	v_and_b32_e32 v176, 0xffff0000, v153
	v_lshlrev_b32_e32 v177, 16, v154
	v_max_f32_e32 v175, v175, v175
	v_max_f32_e32 v176, v176, v176
	v_max_f32_e32 v177, v177, v177
	v_max_f32_e32 v186, 0xda24260, v175
	v_max_f32_e32 v187, 0xda24260, v176
	v_max_f32_e32 v188, 0xda24260, v177
	v_rcp_f32_e32 v176, v186
	v_rcp_f32_e32 v177, v187
	v_lshlrev_b32_e32 v161, 16, v152
	v_and_b32_e32 v174, 0xffff0000, v152
	v_lshlrev_b32_e32 v152, 16, v163
	v_and_b32_e32 v153, 0xffff0000, v163
	v_lshlrev_b32_e32 v181, 16, v166
	v_and_b32_e32 v182, 0xffff0000, v166
	v_lshlrev_b32_e32 v183, 16, v167
	v_and_b32_e32 v184, 0xffff0000, v167
	v_lshlrev_b32_e32 v166, 16, v171
	v_and_b32_e32 v167, 0xffff0000, v171
	v_lshlrev_b32_e32 v171, 16, v168
	v_and_b32_e32 v168, 0xffff0000, v168
	v_max_f32_e32 v161, v161, v161
	v_max_f32_e32 v174, v174, v174
	v_max_f32_e32 v171, v171, v171
	v_max_f32_e32 v168, v168, v168
	v_max_f32_e32 v161, 0xda24260, v161
	v_max_f32_e32 v185, 0xda24260, v174
	v_pk_mul_f32 v[152:153], v[176:177], v[152:153]
	v_and_b32_e32 v178, 0xffff0000, v154
	v_lshlrev_b32_e32 v179, 16, v155
	v_and_b32_e32 v180, 0xffff0000, v155
	v_max_f32_e32 v171, 0xda24260, v171
	v_max_f32_e32 v168, 0xda24260, v168
	v_rcp_f32_e32 v174, v161
	v_rcp_f32_e32 v175, v185
	v_pk_mul_f32 v[20:21], v[20:21], v[152:153]
	v_lshlrev_b32_e32 v152, 16, v169
	v_and_b32_e32 v153, 0xffff0000, v169
	v_max_f32_e32 v178, v178, v178
	v_max_f32_e32 v179, v179, v179
	v_max_f32_e32 v180, v180, v180
	v_max_f32_e32 v181, v181, v181
	v_max_f32_e32 v182, v182, v182
	v_max_f32_e32 v183, v183, v183
	v_max_f32_e32 v184, v184, v184
	v_rcp_f32_e32 v186, v171
	v_rcp_f32_e32 v187, v168
	v_max_f32_e32 v152, v152, v152
	v_max_f32_e32 v153, v153, v153
	v_max_f32_e32 v189, 0xda24260, v178
	v_max_f32_e32 v190, 0xda24260, v179
	v_max_f32_e32 v191, 0xda24260, v180
	v_max_f32_e32 v192, 0xda24260, v181
	v_max_f32_e32 v193, 0xda24260, v182
	v_max_f32_e32 v194, 0xda24260, v183
	v_max_f32_e32 v195, 0xda24260, v184
	v_max_f32_e32 v152, 0xda24260, v152
	v_max_f32_e32 v153, 0xda24260, v153
	v_and_b32_e32 v151, 0xffff0000, v162
	v_rcp_f32_e32 v178, v188
	v_rcp_f32_e32 v179, v189
	v_rcp_f32_e32 v180, v190
	v_rcp_f32_e32 v181, v191
	v_rcp_f32_e32 v182, v192
	v_rcp_f32_e32 v183, v193
	v_rcp_f32_e32 v184, v194
	v_rcp_f32_e32 v185, v195
	v_rcp_f32_e32 v152, v152
	v_rcp_f32_e32 v153, v153
	v_lshlrev_b32_e32 v162, 16, v164
	v_and_b32_e32 v163, 0xffff0000, v164
	v_lshlrev_b32_e32 v154, 16, v165
	v_and_b32_e32 v155, 0xffff0000, v165
	v_lshlrev_b32_e32 v164, 16, v170
	v_and_b32_e32 v165, 0xffff0000, v170
	v_lshlrev_b32_e32 v170, 16, v172
	v_pk_mul_f32 v[150:151], v[174:175], v[150:151]
	v_and_b32_e32 v171, 0xffff0000, v172
	v_pk_mul_f32 v[18:19], v[18:19], v[150:151]
	v_pk_mul_f32 v[150:151], v[186:187], v[170:171]
	v_pk_mul_f32 v[162:163], v[178:179], v[162:163]
	v_pk_mul_f32 v[2:3], v[2:3], v[150:151]
	v_lshlrev_b32_e32 v150, 16, v173
	v_and_b32_e32 v151, 0xffff0000, v173
	v_pk_mul_f32 v[154:155], v[180:181], v[154:155]
	v_pk_mul_f32 v[164:165], v[182:183], v[164:165]
	v_pk_mul_f32 v[166:167], v[184:185], v[166:167]
	v_pk_mul_f32 v[150:151], v[152:153], v[150:151]
	v_pk_mul_f32 v[10:11], v[10:11], v[162:163]
	v_pk_mul_f32 v[12:13], v[12:13], v[154:155]
	v_pk_mul_f32 v[6:7], v[6:7], v[164:165]
	v_pk_mul_f32 v[8:9], v[8:9], v[166:167]
	v_pk_mul_f32 v[4:5], v[4:5], v[150:151]
	s_branch .LBB0_952
